# strategy 7.2: the tile barrier's lgkmcnt(0) moved behind s_barrier (only the next-tile K prefetch reads are outstanding there), on top of v40
# speedup vs baseline: 1.0095x; 1.0011x over previous
; #define LAS __attribute__((address_space(3)))
; template <int MODE, bool FAST> __device__ __forceinline__ bool attn_unit(LAS unsigned char* lds, const AttU& U, const int wv) {
;     ...
;     pb[1][0] = (bf16x8){0, 0, 0, 0, 0, 0, 0, 0}; pb[1][1] = pb[1][0];
;     ATT_QK(0, 0, 0);
;     bf16x8 kpre[NPRE > 0 ? NPRE : 1];
; #pragma unroll
;     for (int i_ = 0; i_ < NPRE; ++i_) kpre[i_] = *(LAS const bf16x8*)(lds + koff + i_ * 32);
.LBB0_441:
	s_and_b32 s48, s33, 2
	s_add_i32 s4, s33, -1
	s_and_b32 s49, s4, 3
	s_mul_i32 s4, s48, 0x4800
	v_add_u32_e32 v168, s4, v184
	s_cmp_eq_u32 s33, 0
	ds_read_b128 v[164:167], v168 offset:96
	s_cselect_b64 s[6:7], -1, 0
	s_mulk_i32 s49, 0x4800
	s_and_b64 s[4:5], s[6:7], exec
	s_cselect_b32 s4, 0, s49
	v_add_u32_e32 v84, s4, v184
	v_exp_f32_e32 v64, v64
	v_exp_f32_e32 v65, v65
	s_nop 0
	v_add_f32_e32 v113, v65, v64
	v_cvt_pk_bf16_f32 v112, v64, v65
	ds_read_b128 v[186:189], v84 offset:9280
	ds_read_b128 v[190:193], v84 offset:9312
	ds_read_b128 v[194:197], v84 offset:13888
	ds_read_b128 v[198:201], v84 offset:13920
	v_mfma_f32_32x32x16_bf16 v[80:95], v[80:83], v[148:151], 0
	v_exp_f32_e32 v64, v66
	v_exp_f32_e32 v65, v67
	v_add_f32_e32 v66, v64, v113
	v_add_f32_e32 v66, v65, v66
	v_cvt_pk_bf16_f32 v113, v64, v65
	v_mfma_f32_32x32x16_bf16 v[80:95], v[108:111], v[152:155], v[80:95]
	v_exp_f32_e32 v64, v68
	v_exp_f32_e32 v65, v69
	v_add_f32_e32 v66, v64, v66
	v_cvt_pk_bf16_f32 v114, v64, v65
	v_add_f32_e32 v64, v65, v66
	v_mfma_f32_32x32x16_bf16 v[80:95], v[104:107], v[156:159], v[80:95]
	v_exp_f32_e32 v65, v70
	v_exp_f32_e32 v66, v71
	v_add_f32_e32 v64, v65, v64
	v_cvt_pk_bf16_f32 v115, v65, v66
	v_add_f32_e32 v64, v66, v64
	s_waitcnt lgkmcnt(4)
	v_mfma_f32_32x32x16_bf16 v[80:95], v[164:167], v[160:163], v[80:95]
	v_exp_f32_e32 v65, v72
	v_exp_f32_e32 v66, v73
	v_add_f32_e32 v64, v65, v64
	v_cvt_pk_bf16_f32 v104, v65, v66
	v_add_f32_e32 v64, v66, v64
	s_waitcnt lgkmcnt(0)
	v_mfma_f32_32x32x16_bf16 v[16:31], v[186:189], v[96:99], v[16:31]
	v_exp_f32_e32 v65, v74
	v_exp_f32_e32 v66, v75
	v_add_f32_e32 v64, v65, v64
	v_cvt_pk_bf16_f32 v105, v65, v66
	v_add_f32_e32 v64, v66, v64
	v_mfma_f32_32x32x16_bf16 v[16:31], v[190:193], v[100:103], v[16:31]
	v_exp_f32_e32 v65, v76
	v_exp_f32_e32 v66, v77
	v_add_f32_e32 v64, v65, v64
	v_cvt_pk_bf16_f32 v106, v65, v66
	v_add_f32_e32 v64, v66, v64
	v_mfma_f32_32x32x16_bf16 v[0:15], v[194:197], v[96:99], v[0:15]
	v_exp_f32_e32 v65, v78
	v_exp_f32_e32 v66, v79
	v_add_f32_e32 v64, v65, v64
	v_cvt_pk_bf16_f32 v107, v65, v66
	v_add_f32_e32 v185, v66, v64
	v_exp_f32_e32 v68, v80
	v_exp_f32_e32 v69, v81
	s_nop 0
	v_add_f32_e32 v80, v69, v68
	v_cvt_pk_bf16_f32 v96, v68, v69
	v_mfma_f32_32x32x16_bf16 v[0:15], v[198:201], v[100:103], v[0:15]
	ds_read_b128 v[64:67], v168 offset:4608
	ds_read_b128 v[164:167], v168 offset:4640
	ds_read_b128 v[108:111], v168 offset:4672
	v_cmp_nge_f32_e64 s[4:5], s62, v185
	v_cmp_gt_f32_e32 vcc, s75, v185
	s_and_b64 vcc, s[6:7], vcc
	s_or_b64 s[4:5], s[4:5], vcc
	ds_read_b128 v[186:189], v168 offset:4704
	s_waitcnt lgkmcnt(1)
	v_mfma_f32_32x32x16_bf16 v[64:79], v[64:67], v[116:119], 0
	ds_read_b128 v[190:193], v168 offset:9216
	ds_read_b128 v[194:197], v168 offset:9248
	ds_read_b128 v[198:201], v168 offset:13824
	ds_read_b128 v[230:233], v168 offset:13856
	v_exp_f32_e32 v81, v82
	v_exp_f32_e32 v82, v83
	v_add_f32_e32 v80, v81, v80
	v_add_f32_e32 v80, v82, v80
	v_cvt_pk_bf16_f32 v97, v81, v82
	v_mfma_f32_32x32x16_bf16 v[64:79], v[164:167], v[120:123], v[64:79]
	v_exp_f32_e32 v81, v84
	v_exp_f32_e32 v82, v85
	v_add_f32_e32 v80, v81, v80
	v_cvt_pk_bf16_f32 v98, v81, v82
	v_add_f32_e32 v80, v82, v80
	v_mfma_f32_32x32x16_bf16 v[64:79], v[108:111], v[124:127], v[64:79]
	v_exp_f32_e32 v81, v86
	v_exp_f32_e32 v82, v87
	v_add_f32_e32 v80, v81, v80
	v_cvt_pk_bf16_f32 v99, v81, v82
	v_add_f32_e32 v80, v82, v80
	s_waitcnt lgkmcnt(4)
	v_mfma_f32_32x32x16_bf16 v[64:79], v[186:189], v[128:131], v[64:79]
	v_exp_f32_e32 v81, v88
	v_exp_f32_e32 v82, v89
	v_add_f32_e32 v80, v81, v80
	v_cvt_pk_bf16_f32 v100, v81, v82
	v_add_f32_e32 v80, v82, v80
	s_waitcnt lgkmcnt(0)
	v_mfma_f32_32x32x16_bf16 v[48:63], v[190:193], v[112:115], v[48:63]
	v_exp_f32_e32 v81, v90
	v_exp_f32_e32 v82, v91
	v_add_f32_e32 v80, v81, v80
	v_cvt_pk_bf16_f32 v101, v81, v82
	v_add_f32_e32 v80, v82, v80
	v_mfma_f32_32x32x16_bf16 v[48:63], v[194:197], v[104:107], v[48:63]
	v_exp_f32_e32 v81, v92
	v_exp_f32_e32 v82, v93
	v_add_f32_e32 v80, v81, v80
	v_cvt_pk_bf16_f32 v102, v81, v82
	v_add_f32_e32 v80, v82, v80
	v_mfma_f32_32x32x16_bf16 v[32:47], v[198:201], v[112:115], v[32:47]
	v_exp_f32_e32 v81, v94
	v_exp_f32_e32 v82, v95
	v_add_f32_e32 v80, v81, v80
	v_cvt_pk_bf16_f32 v103, v81, v82
	v_add_f32_e32 v164, v82, v80
	v_exp_f32_e32 v64, v64
	v_exp_f32_e32 v65, v65
	s_nop 0
	v_add_f32_e32 v165, v65, v64
	v_cvt_pk_bf16_f32 v186, v64, v65
	v_mfma_f32_32x32x16_bf16 v[32:47], v[230:233], v[104:107], v[32:47]
	ds_read_b128 v[80:83], v168 offset:4608
	ds_read_b128 v[112:115], v168 offset:4640
	ds_read_b128 v[108:111], v168 offset:4672
	v_cmp_nge_f32_e64 s[8:9], s62, v164
	v_cmp_gt_f32_e32 vcc, s75, v164
	s_and_b64 s[6:7], s[6:7], vcc
	s_or_b64 s[6:7], s[6:7], s[8:9]
	ds_read_b128 v[104:107], v168 offset:4704
	s_waitcnt lgkmcnt(1)
; #define LAS __attribute__((address_space(3)))
; template <int MODE, bool FAST> __device__ __forceinline__ bool attn_unit(LAS unsigned char* lds, const AttU& U, const int wv) {
;     ...
;     pb[1][0] = (bf16x8){0, 0, 0, 0, 0, 0, 0, 0}; pb[1][1] = pb[1][0];
;     ATT_QK(0, 0, 0);
;     bf16x8 kpre[NPRE > 0 ? NPRE : 1];
; #pragma unroll
;     for (int i_ = 0; i_ < NPRE; ++i_) kpre[i_] = *(LAS const bf16x8*)(lds + koff + i_ * 32);
	v_mfma_f32_32x32x16_bf16 v[80:95], v[80:83], v[148:151], 0
	ds_read_b128 v[190:193], v168 offset:9216
	ds_read_b128 v[194:197], v168 offset:9248
	ds_read_b128 v[198:201], v168 offset:13824
	ds_read_b128 v[230:233], v168 offset:13856
	v_exp_f32_e32 v64, v66
	v_exp_f32_e32 v65, v67
	v_add_f32_e32 v66, v64, v165
	v_add_f32_e32 v66, v65, v66
	v_cvt_pk_bf16_f32 v187, v64, v65
	v_mfma_f32_32x32x16_bf16 v[80:95], v[112:115], v[152:155], v[80:95]
	v_exp_f32_e32 v64, v68
	v_exp_f32_e32 v65, v69
	v_add_f32_e32 v66, v64, v66
	v_cvt_pk_bf16_f32 v188, v64, v65
	v_add_f32_e32 v64, v65, v66
	v_mfma_f32_32x32x16_bf16 v[80:95], v[108:111], v[156:159], v[80:95]
	v_exp_f32_e32 v65, v70
	v_exp_f32_e32 v66, v71
	v_add_f32_e32 v64, v65, v64
	v_cvt_pk_bf16_f32 v189, v65, v66
	v_add_f32_e32 v64, v66, v64
	s_waitcnt lgkmcnt(4)
	v_mfma_f32_32x32x16_bf16 v[80:95], v[104:107], v[160:163], v[80:95]
	v_exp_f32_e32 v65, v72
	v_exp_f32_e32 v66, v73
	v_add_f32_e32 v64, v65, v64
	v_cvt_pk_bf16_f32 v108, v65, v66
	v_add_f32_e32 v64, v66, v64
	s_waitcnt lgkmcnt(0)
	v_mfma_f32_32x32x16_bf16 v[16:31], v[190:193], v[96:99], v[16:31]
	v_exp_f32_e32 v65, v74
	v_exp_f32_e32 v66, v75
	v_add_f32_e32 v64, v65, v64
	v_cvt_pk_bf16_f32 v109, v65, v66
	v_add_f32_e32 v64, v66, v64
	v_mfma_f32_32x32x16_bf16 v[16:31], v[194:197], v[100:103], v[16:31]
	v_exp_f32_e32 v65, v76
	v_exp_f32_e32 v66, v77
	v_add_f32_e32 v64, v65, v64
	v_cvt_pk_bf16_f32 v110, v65, v66
	v_add_f32_e32 v64, v66, v64
	v_mfma_f32_32x32x16_bf16 v[0:15], v[198:201], v[96:99], v[0:15]
	v_exp_f32_e32 v65, v78
	v_exp_f32_e32 v66, v79
	v_add_f32_e32 v64, v65, v64
	v_cvt_pk_bf16_f32 v111, v65, v66
	v_add_f32_e32 v104, v66, v64
	v_exp_f32_e32 v68, v80
	v_exp_f32_e32 v69, v81
	s_nop 0
	v_add_f32_e32 v81, v69, v68
	v_cvt_pk_bf16_f32 v80, v68, v69
	v_mfma_f32_32x32x16_bf16 v[0:15], v[230:233], v[100:103], v[0:15]
	ds_read_b128 v[64:67], v168 offset:18432
	ds_read_b128 v[96:99], v168 offset:18464
	ds_read_b128 v[112:115], v168 offset:18496
	v_cmp_nge_f32_e64 s[8:9], s62, v104
	ds_read_b128 v[100:103], v168 offset:18528
	s_waitcnt lgkmcnt(1)
	v_mfma_f32_32x32x16_bf16 v[64:79], v[64:67], v[116:119], 0
	ds_read_b128 v[190:193], v168 offset:9280
	ds_read_b128 v[194:197], v168 offset:9312
	ds_read_b128 v[198:201], v168 offset:13888
	ds_read_b128 v[230:233], v168 offset:13920
	v_exp_f32_e32 v82, v82
	v_exp_f32_e32 v83, v83
	v_add_f32_e32 v81, v82, v81
	v_add_f32_e32 v105, v83, v81
	v_cvt_pk_bf16_f32 v81, v82, v83
	v_mfma_f32_32x32x16_bf16 v[64:79], v[96:99], v[120:123], v[64:79]
	v_exp_f32_e32 v82, v84
	v_exp_f32_e32 v83, v85
	v_add_f32_e32 v84, v82, v105
	v_cvt_pk_bf16_f32 v82, v82, v83
	v_add_f32_e32 v83, v83, v84
	v_mfma_f32_32x32x16_bf16 v[64:79], v[112:115], v[124:127], v[64:79]
	v_exp_f32_e32 v84, v86
	v_exp_f32_e32 v85, v87
	v_add_f32_e32 v86, v84, v83
	v_cvt_pk_bf16_f32 v83, v84, v85
	v_add_f32_e32 v84, v85, v86
	s_waitcnt lgkmcnt(4)
	v_mfma_f32_32x32x16_bf16 v[64:79], v[100:103], v[128:131], v[64:79]
	v_exp_f32_e32 v85, v88
	v_exp_f32_e32 v86, v89
	v_add_f32_e32 v87, v85, v84
	v_cvt_pk_bf16_f32 v84, v85, v86
	v_add_f32_e32 v85, v86, v87
	s_waitcnt lgkmcnt(0)
	v_mfma_f32_32x32x16_bf16 v[48:63], v[190:193], v[186:189], v[48:63]
	v_exp_f32_e32 v86, v90
	v_exp_f32_e32 v87, v91
	v_add_f32_e32 v88, v86, v85
	v_cvt_pk_bf16_f32 v85, v86, v87
	v_add_f32_e32 v86, v87, v88
	v_mfma_f32_32x32x16_bf16 v[48:63], v[194:197], v[108:111], v[48:63]
	v_exp_f32_e32 v87, v92
	v_exp_f32_e32 v88, v93
	v_add_f32_e32 v89, v87, v86
	v_cvt_pk_bf16_f32 v86, v87, v88
	v_add_f32_e32 v87, v88, v89
	v_mfma_f32_32x32x16_bf16 v[32:47], v[198:201], v[186:189], v[32:47]
	v_exp_f32_e32 v88, v94
	v_exp_f32_e32 v89, v95
	v_add_f32_e32 v90, v88, v87
	v_cvt_pk_bf16_f32 v87, v88, v89
	v_add_f32_e32 v105, v89, v90
	v_mfma_f32_32x32x16_bf16 v[32:47], v[230:233], v[108:111], v[32:47]
	ds_read_b128 v[96:99], v168 offset:18432
	ds_read_b128 v[92:95], v168 offset:18464
	ds_read_b128 v[88:91], v168 offset:18496
	v_cmp_nge_f32_e64 s[10:11], s62, v105
	s_barrier
	s_waitcnt lgkmcnt(0)
	s_cmpk_gt_u32 s33, 0xfc
	s_cbranch_scc1 .LBB0_447
	v_add_u32_e32 v100, s49, v173
	s_waitcnt vmcnt(1)
	ds_write_b128 v100, v[140:143]
	s_waitcnt vmcnt(0)
	ds_write_b128 v100, v[144:147] offset:9216

; #define LAS __attribute__((address_space(3)))
; template <int MODE, bool FAST> __device__ __forceinline__ bool attn_unit(LAS unsigned char* lds, const AttU& U, const int wv) {
;     ...
;     pb[1][0] = (bf16x8){0, 0, 0, 0, 0, 0, 0, 0}; pb[1][1] = pb[1][0];
;     ATT_QK(0, 0, 0);
;     bf16x8 kpre[NPRE > 0 ? NPRE : 1];
; #pragma unroll
;     for (int i_ = 0; i_ < NPRE; ++i_) kpre[i_] = *(LAS const bf16x8*)(lds + koff + i_ * 32);
.LBB0_449:
	v_add_f32_e32 v101, v179, v164
	ds_read_b128 v[164:167], v168 offset:18528
	s_or_b64 s[4:5], s[6:7], s[4:5]
	v_add_f32_e32 v100, v178, v185
	s_or_b64 s[4:5], s[4:5], s[8:9]
	s_or_b64 s[4:5], s[4:5], s[10:11]
	v_add_f32_e32 v182, v100, v104
	v_add_f32_e32 v183, v101, v105
	s_xor_b32 s8, s48, 2
	v_exp_f32_e32 v64, v64
	v_exp_f32_e32 v65, v65
	s_nop 0
	v_add_f32_e32 v185, v65, v64
	v_cvt_pk_bf16_f32 v64, v64, v65
	v_mfma_f32_32x32x16_bf16 v[100:115], v[96:99], v[148:151], 0
	ds_read_b128 v[178:181], v168 offset:9280
	ds_read_b128 v[186:189], v168 offset:9312
	ds_read_b128 v[190:193], v168 offset:13888
	ds_read_b128 v[194:197], v168 offset:13920
	v_exp_f32_e32 v65, v66
	v_exp_f32_e32 v66, v67
	v_add_f32_e32 v67, v65, v185
	v_add_f32_e32 v67, v66, v67
	v_cvt_pk_bf16_f32 v65, v65, v66
	v_mfma_f32_32x32x16_bf16 v[100:115], v[92:95], v[152:155], v[100:115]
	v_exp_f32_e32 v66, v68
	v_exp_f32_e32 v68, v69
	v_add_f32_e32 v67, v66, v67
	v_cvt_pk_bf16_f32 v66, v66, v68
	v_add_f32_e32 v67, v68, v67
	v_mfma_f32_32x32x16_bf16 v[100:115], v[88:91], v[156:159], v[100:115]
	v_exp_f32_e32 v68, v70
	v_exp_f32_e32 v69, v71
	v_add_f32_e32 v70, v68, v67
	v_cvt_pk_bf16_f32 v67, v68, v69
	v_add_f32_e32 v68, v69, v70
	s_waitcnt lgkmcnt(4)
	v_mfma_f32_32x32x16_bf16 v[100:115], v[164:167], v[160:163], v[100:115]
	v_exp_f32_e32 v69, v72
	v_exp_f32_e32 v70, v73
	v_add_f32_e32 v71, v69, v68
	v_cvt_pk_bf16_f32 v68, v69, v70
	v_add_f32_e32 v69, v70, v71
	s_waitcnt lgkmcnt(0)
	v_mfma_f32_32x32x16_bf16 v[16:31], v[178:181], v[80:83], v[16:31]
	v_exp_f32_e32 v70, v74
	v_exp_f32_e32 v71, v75
	v_add_f32_e32 v72, v70, v69
	v_cvt_pk_bf16_f32 v69, v70, v71
	v_add_f32_e32 v70, v71, v72
	v_mfma_f32_32x32x16_bf16 v[16:31], v[186:189], v[84:87], v[16:31]
	v_exp_f32_e32 v71, v76
	v_exp_f32_e32 v72, v77
	v_add_f32_e32 v73, v71, v70
	v_cvt_pk_bf16_f32 v70, v71, v72
	v_add_f32_e32 v71, v72, v73
	v_mfma_f32_32x32x16_bf16 v[0:15], v[190:193], v[80:83], v[0:15]
	v_exp_f32_e32 v72, v78
	v_exp_f32_e32 v73, v79
	v_add_f32_e32 v74, v72, v71
	v_cvt_pk_bf16_f32 v71, v72, v73
	v_add_f32_e32 v198, v73, v74
	v_exp_f32_e32 v88, v100
	v_exp_f32_e32 v89, v101
	s_nop 0
	v_add_f32_e32 v165, v89, v88
	v_cvt_pk_bf16_f32 v164, v88, v89
	v_mfma_f32_32x32x16_bf16 v[0:15], v[194:197], v[84:87], v[0:15]
	ds_read_b128 v[72:75], v168 offset:23040
	ds_read_b128 v[76:79], v168 offset:23072
	ds_read_b128 v[80:83], v168 offset:23104
	v_cmp_nge_f32_e32 vcc, s62, v198
	ds_read_b128 v[84:87], v168 offset:23136
	v_exp_f32_e32 v166, v102
	v_exp_f32_e32 v167, v103
	s_waitcnt lgkmcnt(1)
	v_mfma_f32_32x32x16_bf16 v[88:103], v[72:75], v[116:119], 0
	ds_read_b128 v[178:181], v168 offset:27648
	ds_read_b128 v[186:189], v168 offset:27680
	ds_read_b128 v[190:193], v168 offset:32256
	ds_read_b128 v[194:197], v168 offset:32288
	v_add_f32_e32 v72, v166, v165
	v_add_f32_e32 v72, v167, v72
	v_cvt_pk_bf16_f32 v165, v166, v167
	v_mfma_f32_32x32x16_bf16 v[88:103], v[76:79], v[120:123], v[88:103]
	v_exp_f32_e32 v73, v104
	v_exp_f32_e32 v74, v105
	v_add_f32_e32 v72, v73, v72
	v_cvt_pk_bf16_f32 v166, v73, v74
	v_add_f32_e32 v72, v74, v72
	v_mfma_f32_32x32x16_bf16 v[88:103], v[80:83], v[124:127], v[88:103]
	v_exp_f32_e32 v73, v106
	v_exp_f32_e32 v74, v107
	v_add_f32_e32 v72, v73, v72
	v_cvt_pk_bf16_f32 v167, v73, v74
	v_add_f32_e32 v72, v74, v72
	s_waitcnt lgkmcnt(4)
	v_mfma_f32_32x32x16_bf16 v[88:103], v[84:87], v[128:131], v[88:103]
	v_exp_f32_e32 v73, v108
	v_exp_f32_e32 v74, v109
	v_add_f32_e32 v75, v73, v72
	v_cvt_pk_bf16_f32 v72, v73, v74
	v_add_f32_e32 v73, v74, v75
	s_waitcnt lgkmcnt(0)
	v_mfma_f32_32x32x16_bf16 v[48:63], v[178:181], v[64:67], v[48:63]
	v_exp_f32_e32 v74, v110
	v_exp_f32_e32 v75, v111
	v_add_f32_e32 v76, v74, v73
	v_cvt_pk_bf16_f32 v73, v74, v75
	v_add_f32_e32 v74, v75, v76
	v_mfma_f32_32x32x16_bf16 v[48:63], v[186:189], v[68:71], v[48:63]
	v_exp_f32_e32 v75, v112
	v_exp_f32_e32 v76, v113
	v_add_f32_e32 v77, v75, v74
	v_cvt_pk_bf16_f32 v74, v75, v76
	v_add_f32_e32 v75, v76, v77
	v_mfma_f32_32x32x16_bf16 v[32:47], v[190:193], v[64:67], v[32:47]
	v_exp_f32_e32 v76, v114
	v_exp_f32_e32 v77, v115
	v_add_f32_e32 v78, v76, v75
	v_cvt_pk_bf16_f32 v75, v76, v77
	v_add_f32_e32 v199, v77, v78
	v_exp_f32_e32 v76, v88
	v_exp_f32_e32 v77, v89
	s_nop 0
	v_add_f32_e32 v113, v77, v76
	v_cvt_pk_bf16_f32 v112, v76, v77
	v_mfma_f32_32x32x16_bf16 v[32:47], v[194:197], v[68:71], v[32:47]
	ds_read_b128 v[64:67], v168 offset:23040
	ds_read_b128 v[104:107], v168 offset:23072
	ds_read_b128 v[108:111], v168 offset:23104
	s_or_b64 s[6:7], s[4:5], vcc
	v_cmp_nge_f32_e32 vcc, s62, v199
	v_add_f32_e32 v182, v182, v198
	v_add_f32_e32 v183, v183, v199
	ds_read_b128 v[68:71], v168 offset:23136
	v_exp_f32_e32 v114, v90
	v_exp_f32_e32 v115, v91
	s_waitcnt lgkmcnt(1)
; #define LAS __attribute__((address_space(3)))
; template <int MODE, bool FAST> __device__ __forceinline__ bool attn_unit(LAS unsigned char* lds, const AttU& U, const int wv) {
;     ...
;     pb[1][0] = (bf16x8){0, 0, 0, 0, 0, 0, 0, 0}; pb[1][1] = pb[1][0];
;     ATT_QK(0, 0, 0);
;     bf16x8 kpre[NPRE > 0 ? NPRE : 1];
; #pragma unroll
;     for (int i_ = 0; i_ < NPRE; ++i_) kpre[i_] = *(LAS const bf16x8*)(lds + koff + i_ * 32);
;     ...
;     if constexpr (FAST) {
;         for (int t2 = U.kt0; t2 < U.kt1; t2 += 2) { ATT_TILE(t2, 4, rk, rr, rv); ATT_TILE(t2 + 1, 4, rk2, rr2, rv2); }
	v_mfma_f32_32x32x16_bf16 v[76:91], v[64:67], v[148:151], 0
	ds_read_b128 v[178:181], v168 offset:27648
	ds_read_b128 v[186:189], v168 offset:27680
	ds_read_b128 v[190:193], v168 offset:32256
	ds_read_b128 v[194:197], v168 offset:32288
	v_add_f32_e32 v64, v114, v113
	v_add_f32_e32 v64, v115, v64
	v_cvt_pk_bf16_f32 v113, v114, v115
	v_mfma_f32_32x32x16_bf16 v[76:91], v[104:107], v[152:155], v[76:91]
	v_exp_f32_e32 v65, v92
	v_exp_f32_e32 v66, v93
	v_add_f32_e32 v64, v65, v64
	v_cvt_pk_bf16_f32 v114, v65, v66
	v_add_f32_e32 v64, v66, v64
	v_mfma_f32_32x32x16_bf16 v[76:91], v[108:111], v[156:159], v[76:91]
	v_exp_f32_e32 v65, v94
	v_exp_f32_e32 v66, v95
	v_add_f32_e32 v64, v65, v64
	v_cvt_pk_bf16_f32 v115, v65, v66
	v_add_f32_e32 v64, v66, v64
	s_waitcnt lgkmcnt(4)
	v_mfma_f32_32x32x16_bf16 v[76:91], v[68:71], v[160:163], v[76:91]
	v_exp_f32_e32 v65, v96
	v_exp_f32_e32 v66, v97
	v_add_f32_e32 v64, v65, v64
	v_cvt_pk_bf16_f32 v92, v65, v66
	v_add_f32_e32 v64, v66, v64
	s_waitcnt lgkmcnt(0)
	v_mfma_f32_32x32x16_bf16 v[16:31], v[178:181], v[164:167], v[16:31]
	v_exp_f32_e32 v65, v98
	v_exp_f32_e32 v66, v99
	v_add_f32_e32 v64, v65, v64
	v_cvt_pk_bf16_f32 v93, v65, v66
	v_add_f32_e32 v64, v66, v64
	v_mfma_f32_32x32x16_bf16 v[16:31], v[186:189], v[72:75], v[16:31]
	v_exp_f32_e32 v65, v100
	v_exp_f32_e32 v66, v101
	v_add_f32_e32 v64, v65, v64
	v_cvt_pk_bf16_f32 v94, v65, v66
	v_add_f32_e32 v64, v66, v64
	v_mfma_f32_32x32x16_bf16 v[0:15], v[190:193], v[164:167], v[0:15]
	v_exp_f32_e32 v65, v102
	v_exp_f32_e32 v66, v103
	v_add_f32_e32 v64, v65, v64
	v_cvt_pk_bf16_f32 v95, v65, v66
	v_add_f32_e32 v198, v66, v64
	s_mulk_i32 s8, 0x4800
	v_exp_f32_e32 v68, v76
	v_exp_f32_e32 v69, v77
	s_nop 0
	v_add_f32_e32 v97, v69, v68
	v_cvt_pk_bf16_f32 v96, v68, v69
	v_mfma_f32_32x32x16_bf16 v[0:15], v[194:197], v[72:75], v[0:15]
	v_add_u32_e32 v185, s8, v184
	ds_read_b128 v[64:67], v185
	ds_read_b128 v[100:103], v185 offset:32
	ds_read_b128 v[104:107], v185 offset:64
	v_cmp_nge_f32_e64 s[4:5], s62, v198
	ds_read_b128 v[108:111], v185 offset:96
	s_or_b64 s[6:7], s[6:7], vcc
	v_exp_f32_e32 v98, v78
	v_exp_f32_e32 v99, v79
	s_waitcnt lgkmcnt(1)
	v_mfma_f32_32x32x16_bf16 v[64:79], v[64:67], v[116:119], 0
	ds_read_b128 v[164:167], v168 offset:27712
	ds_read_b128 v[178:181], v168 offset:27744
	ds_read_b128 v[186:189], v168 offset:32320
	ds_read_b128 v[190:193], v168 offset:32352
	v_add_f32_e32 v97, v98, v97
	v_add_f32_e32 v168, v99, v97
	v_cvt_pk_bf16_f32 v97, v98, v99
	v_mfma_f32_32x32x16_bf16 v[64:79], v[100:103], v[120:123], v[64:79]
	v_exp_f32_e32 v80, v80
	v_exp_f32_e32 v81, v81
	v_add_f32_e32 v99, v80, v168
	v_cvt_pk_bf16_f32 v98, v80, v81
	v_add_f32_e32 v80, v81, v99
	v_mfma_f32_32x32x16_bf16 v[64:79], v[104:107], v[124:127], v[64:79]
	v_exp_f32_e32 v81, v82
	v_exp_f32_e32 v82, v83
	v_add_f32_e32 v80, v81, v80
	v_cvt_pk_bf16_f32 v99, v81, v82
	v_add_f32_e32 v80, v82, v80
	s_waitcnt lgkmcnt(4)
	v_mfma_f32_32x32x16_bf16 v[64:79], v[108:111], v[128:131], v[64:79]
	v_exp_f32_e32 v81, v84
	v_exp_f32_e32 v82, v85
	v_add_f32_e32 v80, v81, v80
	v_cvt_pk_bf16_f32 v100, v81, v82
	v_add_f32_e32 v80, v82, v80
	s_waitcnt lgkmcnt(0)
	v_mfma_f32_32x32x16_bf16 v[48:63], v[164:167], v[112:115], v[48:63]
	v_exp_f32_e32 v81, v86
	v_exp_f32_e32 v82, v87
	v_add_f32_e32 v80, v81, v80
	v_cvt_pk_bf16_f32 v101, v81, v82
	v_add_f32_e32 v80, v82, v80
	v_mfma_f32_32x32x16_bf16 v[48:63], v[178:181], v[92:95], v[48:63]
	v_exp_f32_e32 v81, v88
	v_exp_f32_e32 v82, v89
	v_add_f32_e32 v80, v81, v80
	v_cvt_pk_bf16_f32 v102, v81, v82
	v_add_f32_e32 v80, v82, v80
	v_mfma_f32_32x32x16_bf16 v[32:47], v[186:189], v[112:115], v[32:47]
	v_exp_f32_e32 v81, v90
	v_exp_f32_e32 v82, v91
	v_add_f32_e32 v80, v81, v80
	v_cvt_pk_bf16_f32 v103, v81, v82
	v_add_f32_e32 v199, v82, v80
	v_mfma_f32_32x32x16_bf16 v[32:47], v[190:193], v[92:95], v[32:47]
	ds_read_b128 v[80:83], v185
	ds_read_b128 v[108:111], v185 offset:32
	ds_read_b128 v[104:107], v185 offset:64
	s_or_b64 s[4:5], s[6:7], s[4:5]
	v_cmp_nge_f32_e32 vcc, s62, v199
	s_or_b64 s[4:5], s[4:5], vcc
	s_cmp_lg_u64 s[4:5], 0
	s_cselect_b64 s[4:5], -1, 0
	s_or_b64 s[42:43], s[42:43], s[4:5]
	v_add_f32_e32 v178, v182, v198
	v_add_f32_e32 v179, v183, v199
	s_barrier
	s_waitcnt lgkmcnt(0)
	s_add_u32 s46, s46, 0x8000
	s_addc_u32 s47, s47, 0
	s_and_b64 vcc, exec, s[44:45]
	s_cbranch_vccnz .LBB0_451
	s_mov_b32 s33, s14
	s_branch .LBB0_437

.LBB0_927:
	s_add_i32 s6, s61, -1
	s_and_b32 s77, s61, 2
	s_and_b32 s79, s6, 3
	s_cmp_eq_u32 s61, 0
	s_cselect_b64 s[8:9], -1, 0
	s_mulk_i32 s79, 0x5800
	s_and_b64 s[6:7], s[8:9], exec
	s_mul_i32 s78, s77, 0x5800
	s_cselect_b32 s6, 0, s79
	s_add_i32 s76, s78, 0
	v_add_u32_e32 v199, s76, v241
	v_add_u32_e32 v210, s6, v244
	v_exp_f32_e32 v64, v64
	v_exp_f32_e32 v65, v65
	s_nop 0
	v_add_f32_e32 v84, v65, v64
	v_cvt_pk_bf16_f32 v178, v64, v65
	v_exp_f32_e32 v64, v66
	ds_read_b128 v[182:185], v199 offset:96
	ds_read_b128 v[246:249], v199 offset:128
	ds_read_b128 v[250:253], v199 offset:160
	v_exp_f32_e32 v65, v67
	v_add_f32_e32 v66, v64, v84
	v_mfma_f32_32x32x16_bf16 v[80:95], v[80:83], v[122:125], 0
	v_add_f32_e32 v66, v65, v66
	v_cvt_pk_bf16_f32 v179, v64, v65
	v_mfma_f32_32x32x16_bf16 v[80:95], v[174:177], v[126:129], v[80:95]
	v_exp_f32_e32 v64, v68
	v_exp_f32_e32 v65, v69
	v_add_f32_e32 v66, v64, v66
	v_add_f32_e32 v66, v65, v66
	v_cvt_pk_bf16_f32 v180, v64, v65
	v_mfma_f32_32x32x16_bf16 v[80:95], v[170:173], v[130:133], v[80:95]
	v_exp_f32_e32 v64, v70
	v_exp_f32_e32 v65, v71
	v_add_f32_e32 v66, v64, v66
	v_add_f32_e32 v170, v65, v66
	v_cvt_pk_bf16_f32 v181, v64, v65
	s_waitcnt lgkmcnt(0)
	v_mfma_f32_32x32x16_bf16 v[80:95], v[182:185], v[134:137], v[80:95]
	ds_read_b128 v[64:67], v210 offset:13376
	ds_read_b128 v[68:71], v210 offset:13408
	ds_read_b128 v[174:177], v210 offset:17984
	ds_read_b128 v[218:221], v210 offset:18016
	v_exp_f32_e32 v72, v72
	v_exp_f32_e32 v73, v73
	v_add_f32_e32 v170, v72, v170
	v_add_f32_e32 v171, v73, v170
	v_cvt_pk_bf16_f32 v170, v72, v73
	v_mfma_f32_32x32x16_bf16 v[80:95], v[246:249], v[154:157], v[80:95]
	v_exp_f32_e32 v72, v74
	v_exp_f32_e32 v73, v75
	v_add_f32_e32 v74, v72, v171
	v_add_f32_e32 v74, v73, v74
	v_cvt_pk_bf16_f32 v171, v72, v73
	v_mfma_f32_32x32x16_bf16 v[80:95], v[250:253], v[158:161], v[80:95]
	v_exp_f32_e32 v72, v76
	v_exp_f32_e32 v73, v77
	v_add_f32_e32 v74, v72, v74
	v_add_f32_e32 v74, v73, v74
	v_cvt_pk_bf16_f32 v172, v72, v73
	s_waitcnt lgkmcnt(0)
	v_mfma_f32_32x32x16_bf16 v[16:31], v[64:67], v[162:165], v[16:31]
	v_exp_f32_e32 v64, v78
	v_exp_f32_e32 v65, v79
	v_add_f32_e32 v66, v64, v74
	v_add_f32_e32 v246, v65, v66
	v_cvt_pk_bf16_f32 v173, v64, v65
	v_mfma_f32_32x32x16_bf16 v[0:15], v[174:177], v[162:165], v[0:15]
	ds_read_b128 v[64:67], v199 offset:6656
	ds_read_b128 v[182:185], v199 offset:6688
	ds_read_b128 v[174:177], v199 offset:6720
	v_cmp_nge_f32_e64 s[6:7], s48, v246
	v_cmp_gt_f32_e32 vcc, s49, v246
	v_mfma_f32_32x32x16_bf16 v[16:31], v[68:71], v[166:169], v[16:31]
	v_exp_f32_e32 v68, v80
	v_exp_f32_e32 v69, v81
	s_nop 0
	v_add_f32_e32 v70, v69, v68
	v_cvt_pk_bf16_f32 v162, v68, v69
	v_exp_f32_e32 v80, v82
	v_exp_f32_e32 v81, v83
	v_add_f32_e32 v82, v80, v70
	v_mfma_f32_32x32x16_bf16 v[0:15], v[218:221], v[166:169], v[0:15]
	s_and_b64 vcc, s[8:9], vcc
	s_or_b64 s[6:7], s[6:7], vcc
	v_add_u32_e32 v211, s76, v243
	ds_read_b128 v[166:169], v199 offset:6752
	ds_read_b128 v[218:221], v199 offset:6784
	ds_read_b128 v[248:251], v199 offset:6816
	s_waitcnt lgkmcnt(3)
	v_mfma_f32_32x32x16_bf16 v[64:79], v[64:67], v[98:101], 0
	v_add_f32_e32 v82, v81, v82
	v_cvt_pk_bf16_f32 v163, v80, v81
	v_mfma_f32_32x32x16_bf16 v[64:79], v[182:185], v[102:105], v[64:79]
	v_exp_f32_e32 v80, v84
	v_exp_f32_e32 v81, v85
	v_add_f32_e32 v82, v80, v82
	v_add_f32_e32 v82, v81, v82
	v_cvt_pk_bf16_f32 v164, v80, v81
	v_mfma_f32_32x32x16_bf16 v[64:79], v[174:177], v[106:109], v[64:79]
	v_exp_f32_e32 v80, v86
	v_exp_f32_e32 v81, v87
	v_add_f32_e32 v82, v80, v82
	v_add_f32_e32 v174, v81, v82
	v_cvt_pk_bf16_f32 v165, v80, v81
	s_waitcnt lgkmcnt(0)
	v_mfma_f32_32x32x16_bf16 v[64:79], v[166:169], v[110:113], v[64:79]
	ds_read_b128 v[80:83], v211 offset:13312
	ds_read_b128 v[84:87], v211 offset:13344
	ds_read_b128 v[182:185], v211 offset:17920
	ds_read_b128 v[222:225], v211 offset:17952
	v_exp_f32_e32 v88, v88
	v_exp_f32_e32 v89, v89
	v_add_f32_e32 v166, v88, v174
	v_add_f32_e32 v166, v89, v166
	v_cvt_pk_bf16_f32 v174, v88, v89
	v_mfma_f32_32x32x16_bf16 v[64:79], v[218:221], v[114:117], v[64:79]
	v_exp_f32_e32 v88, v90
	v_exp_f32_e32 v89, v91
	v_add_f32_e32 v90, v88, v166
	v_add_f32_e32 v90, v89, v90
	v_cvt_pk_bf16_f32 v175, v88, v89
	v_mfma_f32_32x32x16_bf16 v[64:79], v[248:251], v[118:121], v[64:79]
	v_exp_f32_e32 v88, v92
	v_exp_f32_e32 v89, v93
	v_add_f32_e32 v90, v88, v90
	v_add_f32_e32 v90, v89, v90
	v_cvt_pk_bf16_f32 v176, v88, v89
	s_waitcnt lgkmcnt(0)
	v_mfma_f32_32x32x16_bf16 v[48:63], v[80:83], v[178:181], v[48:63]
	v_exp_f32_e32 v80, v94
	v_exp_f32_e32 v81, v95
	v_add_f32_e32 v82, v80, v90
	v_add_f32_e32 v247, v81, v82
	v_cvt_pk_bf16_f32 v177, v80, v81
	v_mfma_f32_32x32x16_bf16 v[32:47], v[182:185], v[178:181], v[32:47]
	ds_read_b128 v[80:83], v199 offset:6656
	ds_read_b128 v[182:185], v199 offset:6688
	ds_read_b128 v[178:181], v199 offset:6720
	v_cmp_nge_f32_e64 s[10:11], s48, v247
	v_cmp_gt_f32_e32 vcc, s49, v247
	v_mfma_f32_32x32x16_bf16 v[48:63], v[84:87], v[170:173], v[48:63]
	v_exp_f32_e32 v64, v64
	v_exp_f32_e32 v65, v65
	s_nop 0
	v_add_f32_e32 v84, v65, v64
	v_cvt_pk_bf16_f32 v166, v64, v65
	v_exp_f32_e32 v64, v66
	v_exp_f32_e32 v65, v67
	v_add_f32_e32 v66, v64, v84
	v_mfma_f32_32x32x16_bf16 v[32:47], v[222:225], v[170:173], v[32:47]
	s_and_b64 s[8:9], s[8:9], vcc
	s_or_b64 s[8:9], s[8:9], s[10:11]
	ds_read_b128 v[170:173], v199 offset:6752
	ds_read_b128 v[218:221], v199 offset:6784
	ds_read_b128 v[222:225], v199 offset:6816
	s_waitcnt lgkmcnt(3)
; #define LAS __attribute__((address_space(3)))
; template <int MODE, bool FAST> __device__ __forceinline__ bool attn_unit(LAS unsigned char* lds, const AttU& U, const int wv) {
;     ...
;     pb[1][0] = (bf16x8){0, 0, 0, 0, 0, 0, 0, 0}; pb[1][1] = pb[1][0];
;     ATT_QK(0, 0, 0);
;     bf16x8 kpre[NPRE > 0 ? NPRE : 1];
; #pragma unroll
;     for (int i_ = 0; i_ < NPRE; ++i_) kpre[i_] = *(LAS const bf16x8*)(lds + koff + i_ * 32);
	v_mfma_f32_32x32x16_bf16 v[80:95], v[80:83], v[122:125], 0
	v_add_f32_e32 v66, v65, v66
	v_cvt_pk_bf16_f32 v167, v64, v65
	v_mfma_f32_32x32x16_bf16 v[80:95], v[182:185], v[126:129], v[80:95]
	v_exp_f32_e32 v64, v68
	v_exp_f32_e32 v65, v69
	v_add_f32_e32 v66, v64, v66
	v_add_f32_e32 v66, v65, v66
	v_cvt_pk_bf16_f32 v168, v64, v65
	v_mfma_f32_32x32x16_bf16 v[80:95], v[178:181], v[130:133], v[80:95]
	v_exp_f32_e32 v64, v70
	v_exp_f32_e32 v65, v71
	v_add_f32_e32 v66, v64, v66
	v_add_f32_e32 v178, v65, v66
	v_cvt_pk_bf16_f32 v169, v64, v65
	s_waitcnt lgkmcnt(0)
	v_mfma_f32_32x32x16_bf16 v[80:95], v[170:173], v[134:137], v[80:95]
	ds_read_b128 v[64:67], v211 offset:13312
	ds_read_b128 v[68:71], v211 offset:13344
	ds_read_b128 v[182:185], v211 offset:17920
	ds_read_b128 v[248:251], v211 offset:17952
	v_exp_f32_e32 v72, v72
	v_exp_f32_e32 v73, v73
	v_add_f32_e32 v170, v72, v178
	v_add_f32_e32 v170, v73, v170
	v_cvt_pk_bf16_f32 v178, v72, v73
	v_mfma_f32_32x32x16_bf16 v[80:95], v[218:221], v[154:157], v[80:95]
	v_exp_f32_e32 v72, v74
	v_exp_f32_e32 v73, v75
	v_add_f32_e32 v74, v72, v170
	v_add_f32_e32 v74, v73, v74
	v_cvt_pk_bf16_f32 v179, v72, v73
	v_mfma_f32_32x32x16_bf16 v[80:95], v[222:225], v[158:161], v[80:95]
	v_exp_f32_e32 v72, v76
	v_exp_f32_e32 v73, v77
	v_add_f32_e32 v74, v72, v74
	v_add_f32_e32 v74, v73, v74
	v_cvt_pk_bf16_f32 v180, v72, v73
	s_waitcnt lgkmcnt(0)
	v_mfma_f32_32x32x16_bf16 v[16:31], v[64:67], v[162:165], v[16:31]
	v_exp_f32_e32 v64, v78
	v_exp_f32_e32 v65, v79
	v_add_f32_e32 v66, v64, v74
	v_add_f32_e32 v210, v65, v66
	v_cvt_pk_bf16_f32 v181, v64, v65
	v_mfma_f32_32x32x16_bf16 v[0:15], v[182:185], v[162:165], v[0:15]
	v_add_u32_e32 v226, s78, v242
	ds_read_b128 v[64:67], v226 offset:22528
	ds_read_b128 v[170:173], v226 offset:22560
	ds_read_b128 v[182:185], v226 offset:22592
	v_cmp_nge_f32_e64 s[10:11], s48, v210
	v_mfma_f32_32x32x16_bf16 v[16:31], v[68:71], v[174:177], v[16:31]
	v_exp_f32_e32 v68, v80
	v_exp_f32_e32 v69, v81
	s_nop 0
	v_add_f32_e32 v70, v69, v68
	v_cvt_pk_bf16_f32 v162, v68, v69
	v_exp_f32_e32 v80, v82
	v_exp_f32_e32 v81, v83
	v_add_f32_e32 v82, v80, v70
	v_mfma_f32_32x32x16_bf16 v[0:15], v[248:251], v[174:177], v[0:15]
	ds_read_b128 v[174:177], v226 offset:22624
	ds_read_b128 v[218:221], v226 offset:22656
	ds_read_b128 v[222:225], v226 offset:22688
	s_waitcnt lgkmcnt(3)
	v_mfma_f32_32x32x16_bf16 v[64:79], v[64:67], v[98:101], 0
	v_add_f32_e32 v82, v81, v82
	v_cvt_pk_bf16_f32 v163, v80, v81
	v_mfma_f32_32x32x16_bf16 v[64:79], v[170:173], v[102:105], v[64:79]
	v_exp_f32_e32 v80, v84
	v_exp_f32_e32 v81, v85
	v_add_f32_e32 v82, v80, v82
	v_add_f32_e32 v82, v81, v82
	v_cvt_pk_bf16_f32 v164, v80, v81
	v_mfma_f32_32x32x16_bf16 v[64:79], v[182:185], v[106:109], v[64:79]
	v_exp_f32_e32 v80, v86
	v_exp_f32_e32 v81, v87
	v_add_f32_e32 v82, v80, v82
	v_add_f32_e32 v170, v81, v82
	v_cvt_pk_bf16_f32 v165, v80, v81
	s_waitcnt lgkmcnt(0)
	v_mfma_f32_32x32x16_bf16 v[64:79], v[174:177], v[110:113], v[64:79]
	ds_read_b128 v[80:83], v211 offset:13376
	ds_read_b128 v[84:87], v211 offset:13408
	ds_read_b128 v[182:185], v211 offset:17984
	ds_read_b128 v[248:251], v211 offset:18016
	v_exp_f32_e32 v88, v88
	v_exp_f32_e32 v89, v89
	v_add_f32_e32 v170, v88, v170
	v_add_f32_e32 v171, v89, v170
	v_cvt_pk_bf16_f32 v170, v88, v89
	v_mfma_f32_32x32x16_bf16 v[64:79], v[218:221], v[114:117], v[64:79]
	v_exp_f32_e32 v88, v90
	v_exp_f32_e32 v89, v91
	v_add_f32_e32 v90, v88, v171
	v_add_f32_e32 v90, v89, v90
	v_cvt_pk_bf16_f32 v171, v88, v89
	v_mfma_f32_32x32x16_bf16 v[64:79], v[222:225], v[118:121], v[64:79]
	v_exp_f32_e32 v88, v92
	v_exp_f32_e32 v89, v93
	v_add_f32_e32 v90, v88, v90
	v_add_f32_e32 v90, v89, v90
	v_cvt_pk_bf16_f32 v172, v88, v89
	s_waitcnt lgkmcnt(0)
	v_mfma_f32_32x32x16_bf16 v[48:63], v[80:83], v[166:169], v[48:63]
	v_exp_f32_e32 v80, v94
	v_exp_f32_e32 v81, v95
	v_add_f32_e32 v82, v80, v90
	v_add_f32_e32 v211, v81, v82
	v_cvt_pk_bf16_f32 v173, v80, v81
	v_mfma_f32_32x32x16_bf16 v[32:47], v[182:185], v[166:169], v[32:47]
	ds_read_b128 v[80:83], v226 offset:22528
	ds_read_b128 v[182:185], v226 offset:22560
	ds_read_b128 v[174:177], v226 offset:22592
	v_cmp_nge_f32_e64 s[12:13], s48, v211
	v_mfma_f32_32x32x16_bf16 v[48:63], v[84:87], v[178:181], v[48:63]
	s_barrier
	s_waitcnt lgkmcnt(0)
	v_mfma_f32_32x32x16_bf16 v[32:47], v[248:251], v[178:181], v[32:47]
	s_cmpk_gt_u32 s61, 0xfc
	s_cbranch_scc1 .LBB0_933
	s_add_i32 s24, s79, 0
	v_add_u32_e32 v84, s24, v238
	v_add_u32_e32 v85, s24, v245
	v_add_u32_e32 v86, s24, v198
	s_waitcnt vmcnt(1)
	ds_write_b128 v84, v[150:153]
	s_waitcnt vmcnt(0)
	ds_write_b64 v85, v[190:191] offset:128
	ds_write_b128 v86, v[138:141] offset:13312

; #define LAS __attribute__((address_space(3)))
; template <int MODE, bool FAST> __device__ __forceinline__ bool attn_unit(LAS unsigned char* lds, const AttU& U, const int wv) {
;     ...
;     pb[1][0] = (bf16x8){0, 0, 0, 0, 0, 0, 0, 0}; pb[1][1] = pb[1][0];
;     ATT_QK(0, 0, 0);
;     bf16x8 kpre[NPRE > 0 ? NPRE : 1];
; #pragma unroll
;     for (int i_ = 0; i_ < NPRE; ++i_) kpre[i_] = *(LAS const bf16x8*)(lds + koff + i_ * 32);
.LBB0_935:
	s_or_b64 s[6:7], s[8:9], s[6:7]
	v_add_f32_e32 v84, v204, v246
	v_add_f32_e32 v85, v205, v247
	s_or_b64 s[6:7], s[6:7], s[10:11]
	s_or_b64 s[6:7], s[6:7], s[12:13]
	v_add_f32_e32 v178, v84, v210
	v_add_f32_e32 v179, v85, v211
	s_xor_b32 s10, s77, 2
	v_add_u32_e32 v222, s78, v244
	v_exp_f32_e32 v64, v64
	v_exp_f32_e32 v65, v65
	s_nop 0
	v_add_f32_e32 v84, v65, v64
	v_cvt_pk_bf16_f32 v166, v64, v65
	v_exp_f32_e32 v64, v66
	ds_read_b128 v[204:207], v199 offset:22624
	ds_read_b128 v[208:211], v199 offset:22656
	ds_read_b128 v[218:221], v199 offset:22688
	v_exp_f32_e32 v65, v67
	v_add_f32_e32 v66, v64, v84
	v_mfma_f32_32x32x16_bf16 v[80:95], v[80:83], v[122:125], 0
	v_add_f32_e32 v66, v65, v66
	v_cvt_pk_bf16_f32 v167, v64, v65
	v_mfma_f32_32x32x16_bf16 v[80:95], v[182:185], v[126:129], v[80:95]
	v_exp_f32_e32 v64, v68
	v_exp_f32_e32 v65, v69
	v_add_f32_e32 v66, v64, v66
	v_add_f32_e32 v66, v65, v66
	v_cvt_pk_bf16_f32 v168, v64, v65
	v_mfma_f32_32x32x16_bf16 v[80:95], v[174:177], v[130:133], v[80:95]
	v_exp_f32_e32 v64, v70
	v_exp_f32_e32 v65, v71
	v_add_f32_e32 v66, v64, v66
	v_add_f32_e32 v174, v65, v66
	v_cvt_pk_bf16_f32 v169, v64, v65
	s_waitcnt lgkmcnt(0)
	v_mfma_f32_32x32x16_bf16 v[80:95], v[204:207], v[134:137], v[80:95]
	ds_read_b128 v[64:67], v222 offset:13376
	ds_read_b128 v[68:71], v222 offset:13408
	ds_read_b128 v[180:183], v222 offset:17984
	ds_read_b128 v[222:225], v222 offset:18016
	v_exp_f32_e32 v72, v72
	v_exp_f32_e32 v73, v73
	v_add_f32_e32 v174, v72, v174
	v_add_f32_e32 v175, v73, v174
	v_cvt_pk_bf16_f32 v174, v72, v73
	v_mfma_f32_32x32x16_bf16 v[80:95], v[208:211], v[154:157], v[80:95]
	v_exp_f32_e32 v72, v74
	v_exp_f32_e32 v73, v75
	v_add_f32_e32 v74, v72, v175
	v_add_f32_e32 v74, v73, v74
	v_cvt_pk_bf16_f32 v175, v72, v73
	v_mfma_f32_32x32x16_bf16 v[80:95], v[218:221], v[158:161], v[80:95]
	v_exp_f32_e32 v72, v76
	v_exp_f32_e32 v73, v77
	v_add_f32_e32 v74, v72, v74
	v_add_f32_e32 v74, v73, v74
	v_cvt_pk_bf16_f32 v176, v72, v73
	s_waitcnt lgkmcnt(0)
	v_mfma_f32_32x32x16_bf16 v[16:31], v[64:67], v[162:165], v[16:31]
	v_exp_f32_e32 v64, v78
	v_exp_f32_e32 v65, v79
	v_add_f32_e32 v66, v64, v74
	v_add_f32_e32 v204, v65, v66
	v_cvt_pk_bf16_f32 v177, v64, v65
	v_mfma_f32_32x32x16_bf16 v[0:15], v[180:183], v[162:165], v[0:15]
	ds_read_b128 v[64:67], v199 offset:29184
	ds_read_b128 v[180:183], v199 offset:29216
	ds_read_b128 v[208:211], v199 offset:29248
	v_cmp_nge_f32_e32 vcc, s48, v204
	v_mfma_f32_32x32x16_bf16 v[16:31], v[68:71], v[170:173], v[16:31]
	v_mfma_f32_32x32x16_bf16 v[0:15], v[222:225], v[170:173], v[0:15]
	v_mad_u32_u24 v68, v187, s69, v186
	v_add_u32_e32 v206, s76, v68
	v_exp_f32_e32 v68, v80
	v_exp_f32_e32 v69, v81
	s_nop 0
	v_add_f32_e32 v70, v69, v68
	v_cvt_pk_bf16_f32 v162, v68, v69
	v_exp_f32_e32 v80, v82
	ds_read_b128 v[170:173], v199 offset:29280
	ds_read_b128 v[218:221], v199 offset:29312
	ds_read_b128 v[222:225], v199 offset:29344
	v_exp_f32_e32 v81, v83
	v_add_f32_e32 v82, v80, v70
	s_waitcnt lgkmcnt(3)
	v_mfma_f32_32x32x16_bf16 v[64:79], v[64:67], v[98:101], 0
	v_add_f32_e32 v82, v81, v82
	v_cvt_pk_bf16_f32 v163, v80, v81
	v_mfma_f32_32x32x16_bf16 v[64:79], v[180:183], v[102:105], v[64:79]
	v_exp_f32_e32 v80, v84
	v_exp_f32_e32 v81, v85
	v_add_f32_e32 v82, v80, v82
	v_add_f32_e32 v82, v81, v82
	v_cvt_pk_bf16_f32 v164, v80, v81
	v_mfma_f32_32x32x16_bf16 v[64:79], v[208:211], v[106:109], v[64:79]
	v_exp_f32_e32 v80, v86
	v_exp_f32_e32 v81, v87
	v_add_f32_e32 v82, v80, v82
	v_add_f32_e32 v184, v81, v82
	v_cvt_pk_bf16_f32 v165, v80, v81
	s_waitcnt lgkmcnt(0)
	v_mfma_f32_32x32x16_bf16 v[64:79], v[170:173], v[110:113], v[64:79]
	ds_read_b128 v[80:83], v206 offset:35840
	ds_read_b128 v[84:87], v206 offset:35872
	ds_read_b128 v[180:183], v206 offset:40448
	ds_read_b128 v[208:211], v206 offset:40480
	v_exp_f32_e32 v88, v88
	v_exp_f32_e32 v89, v89
	v_add_f32_e32 v170, v88, v184
	v_add_f32_e32 v171, v89, v170
	v_cvt_pk_bf16_f32 v170, v88, v89
	v_mfma_f32_32x32x16_bf16 v[64:79], v[218:221], v[114:117], v[64:79]
	v_exp_f32_e32 v88, v90
	v_exp_f32_e32 v89, v91
	v_add_f32_e32 v90, v88, v171
	v_add_f32_e32 v90, v89, v90
	v_cvt_pk_bf16_f32 v171, v88, v89
	v_mfma_f32_32x32x16_bf16 v[64:79], v[222:225], v[118:121], v[64:79]
	v_exp_f32_e32 v88, v92
	v_exp_f32_e32 v89, v93
	v_add_f32_e32 v90, v88, v90
	v_add_f32_e32 v90, v89, v90
	v_cvt_pk_bf16_f32 v172, v88, v89
	s_waitcnt lgkmcnt(0)
	v_mfma_f32_32x32x16_bf16 v[48:63], v[80:83], v[166:169], v[48:63]
	v_exp_f32_e32 v80, v94
	v_exp_f32_e32 v81, v95
	v_add_f32_e32 v82, v80, v90
	v_add_f32_e32 v205, v81, v82
	v_cvt_pk_bf16_f32 v173, v80, v81
	v_mfma_f32_32x32x16_bf16 v[32:47], v[180:183], v[166:169], v[32:47]
	ds_read_b128 v[80:83], v199 offset:29184
	ds_read_b128 v[166:169], v199 offset:29216
	ds_read_b128 v[182:185], v199 offset:29248
	s_or_b64 s[8:9], s[6:7], vcc
	v_cmp_nge_f32_e32 vcc, s48, v205
	v_add_f32_e32 v204, v178, v204
	v_add_f32_e32 v205, v179, v205
	v_mfma_f32_32x32x16_bf16 v[48:63], v[84:87], v[174:177], v[48:63]
	v_exp_f32_e32 v64, v64
	v_exp_f32_e32 v65, v65
	s_nop 0
	v_add_f32_e32 v84, v65, v64
	v_cvt_pk_bf16_f32 v178, v64, v65
	v_exp_f32_e32 v64, v66
	v_exp_f32_e32 v65, v67
	v_add_f32_e32 v66, v64, v84
	v_mfma_f32_32x32x16_bf16 v[32:47], v[208:211], v[174:177], v[32:47]
	ds_read_b128 v[174:177], v199 offset:29280
	ds_read_b128 v[208:211], v199 offset:29312
	ds_read_b128 v[218:221], v199 offset:29344
	s_waitcnt lgkmcnt(3)
; #define LAS __attribute__((address_space(3)))
; template <int MODE, bool FAST> __device__ __forceinline__ bool attn_unit(LAS unsigned char* lds, const AttU& U, const int wv) {
;     ...
;     pb[1][0] = (bf16x8){0, 0, 0, 0, 0, 0, 0, 0}; pb[1][1] = pb[1][0];
;     ATT_QK(0, 0, 0);
;     bf16x8 kpre[NPRE > 0 ? NPRE : 1];
; #pragma unroll
;     for (int i_ = 0; i_ < NPRE; ++i_) kpre[i_] = *(LAS const bf16x8*)(lds + koff + i_ * 32);
;     ...
;     if constexpr (FAST) {
;         for (int t2 = U.kt0; t2 < U.kt1; t2 += 2) { ATT_TILE(t2, 4, rk, rr, rv); ATT_TILE(t2 + 1, 4, rk2, rr2, rv2); }
	v_mfma_f32_32x32x16_bf16 v[80:95], v[80:83], v[122:125], 0
	v_add_f32_e32 v66, v65, v66
	v_cvt_pk_bf16_f32 v179, v64, v65
	v_mfma_f32_32x32x16_bf16 v[80:95], v[166:169], v[126:129], v[80:95]
	v_exp_f32_e32 v64, v68
	v_exp_f32_e32 v65, v69
	v_add_f32_e32 v66, v64, v66
	v_add_f32_e32 v66, v65, v66
	v_cvt_pk_bf16_f32 v180, v64, v65
	v_mfma_f32_32x32x16_bf16 v[80:95], v[182:185], v[130:133], v[80:95]
	v_exp_f32_e32 v64, v70
	v_exp_f32_e32 v65, v71
	v_add_f32_e32 v66, v64, v66
	v_add_f32_e32 v182, v65, v66
	v_cvt_pk_bf16_f32 v181, v64, v65
	s_waitcnt lgkmcnt(0)
	v_mfma_f32_32x32x16_bf16 v[80:95], v[174:177], v[134:137], v[80:95]
	ds_read_b128 v[64:67], v206 offset:35840
	ds_read_b128 v[68:71], v206 offset:35872
	ds_read_b128 v[166:169], v206 offset:40448
	ds_read_b128 v[222:225], v206 offset:40480
	v_exp_f32_e32 v72, v72
	v_exp_f32_e32 v73, v73
	v_add_f32_e32 v174, v72, v182
	v_add_f32_e32 v174, v73, v174
	v_cvt_pk_bf16_f32 v182, v72, v73
	v_mfma_f32_32x32x16_bf16 v[80:95], v[208:211], v[154:157], v[80:95]
	v_exp_f32_e32 v72, v74
	v_exp_f32_e32 v73, v75
	v_add_f32_e32 v74, v72, v174
	v_add_f32_e32 v74, v73, v74
	v_cvt_pk_bf16_f32 v183, v72, v73
	v_mfma_f32_32x32x16_bf16 v[80:95], v[218:221], v[158:161], v[80:95]
	v_exp_f32_e32 v72, v76
	v_exp_f32_e32 v73, v77
	v_add_f32_e32 v74, v72, v74
	v_add_f32_e32 v74, v73, v74
	v_cvt_pk_bf16_f32 v184, v72, v73
	s_waitcnt lgkmcnt(0)
	v_mfma_f32_32x32x16_bf16 v[16:31], v[64:67], v[162:165], v[16:31]
	v_exp_f32_e32 v64, v78
	v_exp_f32_e32 v65, v79
	v_add_f32_e32 v66, v64, v74
	v_add_f32_e32 v226, v65, v66
	v_cvt_pk_bf16_f32 v185, v64, v65
	v_mfma_f32_32x32x16_bf16 v[0:15], v[166:169], v[162:165], v[0:15]
	s_mulk_i32 s10, 0x5800
	v_add_u32_e32 v199, s10, v242
	ds_read_b128 v[64:67], v199
	ds_read_b128 v[164:167], v199 offset:32
	ds_read_b128 v[174:177], v199 offset:64
	v_cmp_nge_f32_e64 s[6:7], s48, v226
	v_mfma_f32_32x32x16_bf16 v[16:31], v[68:71], v[170:173], v[16:31]
	v_exp_f32_e32 v68, v80
	v_exp_f32_e32 v69, v81
	s_nop 0
	v_add_f32_e32 v70, v69, v68
	v_cvt_pk_bf16_f32 v162, v68, v69
	v_exp_f32_e32 v80, v82
	v_exp_f32_e32 v81, v83
	v_add_f32_e32 v82, v80, v70
	v_mfma_f32_32x32x16_bf16 v[0:15], v[222:225], v[170:173], v[0:15]
	s_or_b64 s[8:9], s[8:9], vcc
	ds_read_b128 v[168:171], v199 offset:96
	ds_read_b128 v[208:211], v199 offset:128
	ds_read_b128 v[218:221], v199 offset:160
	s_waitcnt lgkmcnt(3)
	v_mfma_f32_32x32x16_bf16 v[64:79], v[64:67], v[98:101], 0
	v_add_f32_e32 v82, v81, v82
	v_cvt_pk_bf16_f32 v163, v80, v81
	v_mfma_f32_32x32x16_bf16 v[64:79], v[164:167], v[102:105], v[64:79]
	v_exp_f32_e32 v80, v84
	v_exp_f32_e32 v81, v85
	v_add_f32_e32 v82, v80, v82
	v_add_f32_e32 v82, v81, v82
	v_cvt_pk_bf16_f32 v164, v80, v81
	v_mfma_f32_32x32x16_bf16 v[64:79], v[174:177], v[106:109], v[64:79]
	v_exp_f32_e32 v80, v86
	v_exp_f32_e32 v81, v87
	v_add_f32_e32 v82, v80, v82
	v_add_f32_e32 v166, v81, v82
	v_cvt_pk_bf16_f32 v165, v80, v81
	s_waitcnt lgkmcnt(0)
	v_mfma_f32_32x32x16_bf16 v[64:79], v[168:171], v[110:113], v[64:79]
	ds_read_b128 v[80:83], v206 offset:35904
	ds_read_b128 v[84:87], v206 offset:35936
	ds_read_b128 v[222:225], v206 offset:40512
	ds_read_b128 v[246:249], v206 offset:40544
	v_exp_f32_e32 v88, v88
	v_exp_f32_e32 v89, v89
	v_add_f32_e32 v166, v88, v166
	v_add_f32_e32 v167, v89, v166
	v_cvt_pk_bf16_f32 v166, v88, v89
	v_mfma_f32_32x32x16_bf16 v[64:79], v[208:211], v[114:117], v[64:79]
	v_exp_f32_e32 v88, v90
	v_exp_f32_e32 v89, v91
	v_add_f32_e32 v90, v88, v167
	v_add_f32_e32 v90, v89, v90
	v_cvt_pk_bf16_f32 v167, v88, v89
	v_mfma_f32_32x32x16_bf16 v[64:79], v[218:221], v[118:121], v[64:79]
	v_exp_f32_e32 v88, v92
	v_exp_f32_e32 v89, v93
	v_add_f32_e32 v90, v88, v90
	v_add_f32_e32 v90, v89, v90
	v_cvt_pk_bf16_f32 v168, v88, v89
	s_waitcnt lgkmcnt(0)
	v_mfma_f32_32x32x16_bf16 v[48:63], v[80:83], v[178:181], v[48:63]
	v_exp_f32_e32 v80, v94
	v_exp_f32_e32 v81, v95
	v_add_f32_e32 v82, v80, v90
	v_add_f32_e32 v227, v81, v82
	v_cvt_pk_bf16_f32 v169, v80, v81
	v_mfma_f32_32x32x16_bf16 v[32:47], v[222:225], v[178:181], v[32:47]
	ds_read_b128 v[80:83], v199
	ds_read_b128 v[174:177], v199 offset:32
	ds_read_b128 v[170:173], v199 offset:64
	s_or_b64 s[6:7], s[8:9], s[6:7]
	v_cmp_nge_f32_e32 vcc, s48, v227
	s_or_b64 s[6:7], s[6:7], vcc
	s_cmp_lg_u64 s[6:7], 0
	s_cselect_b64 s[6:7], -1, 0
	s_or_b64 s[42:43], s[42:43], s[6:7]
	v_mfma_f32_32x32x16_bf16 v[48:63], v[84:87], v[182:185], v[48:63]
	v_add_f32_e64 v204, v204, v226
	v_add_f32_e64 v205, v205, v227
	s_barrier
	s_waitcnt lgkmcnt(0)
	v_mfma_f32_32x32x16_bf16 v[32:47], v[246:249], v[182:185], v[32:47]
	s_add_u32 s40, s40, 0x40000
	s_mov_b64 s[6:7], 0x2000
	s_addc_u32 s41, s41, 0
	v_lshl_add_u64 v[202:203], v[202:203], 0, s[6:7]
	s_and_b64 vcc, exec, s[44:45]
	s_cbranch_vccnz .LBB0_937
	s_mov_b32 s61, s30
	s_branch .LBB0_923
